# attention: scores of the next key tile (QK) accumulate in a second register set under the current tile's softmax; K tiles staged two ahead; loop unrolled by two
# baseline (speedup 1.0000x reference)
.LBB0_536:
	s_and_b64 vcc, exec, s[6:7]
	s_cbranch_vccz .LBB0_519
	s_ashr_i32 s53, s52, 5
	s_waitcnt vmcnt(14)
	v_mov_b32_e32 v2, v152
	s_sub_i32 s54, 15, s53
	s_lshl_b32 s71, s54, 8
	v_ashrrev_i32_e32 v0, 1, v2
	v_and_b32_e32 v102, 0xffffffe0, v0
	v_and_b32_e32 v116, 31, v2
	v_add_u32_e32 v103, s71, v102
	v_or_b32_e32 v104, v103, v116
	s_lshl_b32 s6, s52, 9
	s_and_b32 s14, s6, 0x3000
	v_ashrrev_i32_e32 v105, 31, v104
	v_lshl_add_u64 v[0:1], v[104:105], 0, s[14:15]
	s_waitcnt vmcnt(13)
	v_bfe_u32 v3, v2, 5, 1
	s_waitcnt vmcnt(11)
	v_lshlrev_b64 v[4:5], 6, v[0:1]
	s_waitcnt vmcnt(9)
	v_lshl_add_u64 v[6:7], s[24:25], 0, v[4:5]
	s_waitcnt vmcnt(8)
	v_lshlrev_b32_e32 v8, 5, v3
	s_waitcnt vmcnt(7)
	v_mov_b32_e32 v9, v101
	v_lshl_add_u64 v[4:5], s[26:27], 0, v[4:5]
	v_mov_b64_e32 v[20:21], s[42:43]
	s_waitcnt vmcnt(3)
	v_lshl_add_u64 v[12:13], v[6:7], 0, v[8:9]
	s_waitcnt vmcnt(0)
	v_lshl_add_u64 v[16:17], v[4:5], 0, v[8:9]
	s_and_b32 s72, s52, 7
	v_mad_u64_u32 v[20:21], s[6:7], v0, s66, v[20:21]
	global_load_dwordx4 v[4:7], v[16:17], off
	global_load_dwordx4 v[8:11], v[12:13], off
	s_nop 0
	global_load_dwordx4 v[12:15], v[12:13], off offset:16
	s_nop 0
	global_load_dwordx4 v[16:19], v[16:17], off offset:16
	v_mad_i32_i24 v21, v1, s66, v21
	s_mul_i32 s6, s72, 0xc0
	s_mov_b32 s7, s15
	v_lshl_add_u64 v[0:1], v[20:21], 0, s[6:7]
	v_lshlrev_b32_e32 v100, 4, v3
	v_lshl_add_u64 v[0:1], v[0:1], 0, v[100:101]
	global_load_dwordx4 v[20:23], v[0:1], off offset:128
	global_load_dwordx4 v[24:27], v[0:1], off offset:160
	global_load_dwordx4 v[64:67], v[0:1], off
	global_load_dwordx4 v[68:71], v[0:1], off offset:32
	global_load_dwordx4 v[72:75], v[0:1], off offset:64
	global_load_dwordx4 v[76:79], v[0:1], off offset:96
	s_lshl_b32 s10, s72, 8
	s_mov_b32 s11, s15
	v_cmp_gt_i32_e64 s[6:7], s67, v2
	s_waitcnt vmcnt(9)
	v_mov_b32_e32 v0, v4
	s_waitcnt vmcnt(8)
	v_mov_b32_e32 v1, v8
	v_mov_b32_e32 v28, v8
	v_mov_b32_e32 v29, v4
	v_mov_b32_e32 v8, v5
	s_waitcnt vmcnt(5)
	v_lshlrev_b32_e32 v39, 16, v20
	s_waitcnt vmcnt(4)
	v_lshlrev_b32_e32 v38, 16, v24
	v_mov_b32_e32 v30, v6
	v_mov_b32_e32 v31, v10
	v_mov_b32_e32 v32, v10
	v_mov_b32_e32 v33, v6
	v_mov_b32_e32 v10, v7
	v_mov_b32_e32 v6, v11
	v_mov_b32_e32 v34, v16
	v_mov_b32_e32 v35, v12
	v_mov_b32_e32 v36, v12
	v_mov_b32_e32 v12, v17
	v_and_b32_e32 v41, 0xffff0000, v20
	v_and_b32_e32 v40, 0xffff0000, v24
	v_lshlrev_b32_e32 v43, 16, v21
	v_lshlrev_b32_e32 v42, 16, v25
	v_and_b32_e32 v21, 0xffff0000, v21
	v_and_b32_e32 v20, 0xffff0000, v25
	v_lshlrev_b32_e32 v25, 16, v22
	v_lshlrev_b32_e32 v24, 16, v26
	v_and_b32_e32 v45, 0xffff0000, v22
	v_and_b32_e32 v44, 0xffff0000, v26
	v_pk_mul_f32 v[0:1], v[0:1], v[38:39]
	v_mov_b32_e32 v4, v9
	v_pk_mul_f32 v[28:29], v[28:29], v[38:39]
	v_pk_mul_f32 v[8:9], v[8:9], v[40:41]
	v_pk_mul_f32 v[10:11], v[10:11], v[20:21]
	v_pk_mul_f32 v[6:7], v[6:7], v[20:21]
	v_pk_mul_f32 v[20:21], v[34:35], v[24:25]
	v_pk_mul_f32 v[34:35], v[12:13], v[44:45]
	v_sub_f32_e32 v0, v1, v0
	v_mov_b32_e32 v37, v16
	v_pk_mul_f32 v[4:5], v[4:5], v[40:41]
	v_pk_mul_f32 v[30:31], v[30:31], v[42:43]
	v_pk_mul_f32 v[32:33], v[32:33], v[42:43]
	v_add_f32_e32 v1, v28, v29
	v_sub_f32_e32 v8, v9, v8
	v_cvt_pk_bf16_f32 v80, v0, v8
	v_sub_f32_e32 v0, v35, v34
	v_mov_b32_e32 v16, v13
	v_add_f32_e32 v4, v4, v5
	v_sub_f32_e32 v5, v31, v30
	v_add_f32_e32 v9, v32, v33
	v_sub_f32_e32 v10, v11, v10
	v_add_f32_e32 v6, v6, v7
	v_sub_f32_e32 v7, v21, v20
	v_cvt_pk_bf16_f32 v84, v1, v4
	v_cvt_pk_bf16_f32 v81, v5, v10
	v_cvt_pk_bf16_f32 v85, v9, v6
	v_cvt_pk_bf16_f32 v82, v7, v0
	v_pk_mul_f32 v[0:1], v[16:17], v[44:45]
	v_pk_mul_f32 v[24:25], v[36:37], v[24:25]
	v_add_f32_e32 v0, v0, v1
	v_add_f32_e32 v11, v24, v25
	v_cvt_pk_bf16_f32 v86, v11, v0
	v_lshlrev_b32_e32 v1, 16, v23
	v_lshlrev_b32_e32 v0, 16, v27
	v_mov_b32_e32 v4, v18
	v_mov_b32_e32 v5, v14
	v_pk_mul_f32 v[4:5], v[4:5], v[0:1]
	v_lshlrev_b32_e32 v10, 3, v2
	v_sub_f32_e32 v6, v5, v4
	v_mov_b32_e32 v4, v14
	v_mov_b32_e32 v5, v18
	v_pk_mul_f32 v[0:1], v[4:5], v[0:1]
	v_mov_b32_e32 v14, v19
	v_add_f32_e32 v7, v0, v1
	v_and_b32_e32 v1, 0xffff0000, v23
	v_and_b32_e32 v0, 0xffff0000, v27
	v_mov_b32_e32 v18, v15
	v_pk_mul_f32 v[4:5], v[14:15], v[0:1]
	v_pk_mul_f32 v[0:1], v[18:19], v[0:1]
	v_sub_f32_e32 v4, v5, v4
	v_add_f32_e32 v0, v0, v1
	v_cvt_pk_bf16_f32 v83, v6, v4
	v_cvt_pk_bf16_f32 v87, v7, v0
	v_ashrrev_i32_e32 v0, 3, v2
	v_ashrrev_i32_e32 v1, 31, v0
	v_lshl_add_u64 v[4:5], v[0:1], 0, s[14:15]
	v_lshlrev_b64 v[4:5], 11, v[4:5]
	v_lshl_add_u64 v[4:5], s[44:45], 0, v[4:5]
	v_lshl_add_u64 v[6:7], v[4:5], 0, s[10:11]
	v_and_b32_e32 v5, 56, v10
	v_lshlrev_b32_e32 v8, 1, v5
	v_mov_b32_e32 v9, v101
	v_lshl_add_u64 v[6:7], v[6:7], 0, v[8:9]
	global_load_dwordx4 v[88:91], v[6:7], off
	v_and_b32_e32 v160, 63, v2
	v_mov_b32_e32 v161, 0
	v_lshrrev_b32_e32 v162, 6, v2
	v_mov_b32_e32 v163, 0
	v_lshl_add_u64 v[166:167], v[160:161], 0, s[14:15]
	v_lshlrev_b64 v[166:167], 11, v[166:167]
	v_mul_u32_u24_e32 v159, 0x480, v162
	v_lshlrev_b32_e32 v162, 4, v162
	v_lshl_add_u64 v[164:165], s[44:45], 0, v[166:167]
	v_lshl_add_u64 v[164:165], v[164:165], 0, s[10:11]
	v_lshl_add_u64 v[164:165], v[164:165], 0, v[162:163]
	v_lshl_add_u32 v158, v160, 1, v159
	v_lshlrev_b64 v[166:167], 11, v[160:161]
	global_load_dwordx4 v[92:95], v[164:165], off offset:128
	v_lshl_add_u64 v[150:151], v[6:7], 0, s[50:51]
	global_load_dwordx4 v[250:253], v[150:151], off
	v_bfe_u32 v4, v2, 2, 6
	v_and_b32_e32 v6, 24, v10
	s_and_saveexec_b64 s[8:9], s[6:7]
	s_cbranch_execz .LBB0_539
	v_or_b32_e32 v7, s14, v4
	v_lshlrev_b32_e32 v8, 6, v7
	v_mov_b32_e32 v9, v101
	v_lshl_add_u64 v[8:9], s[46:47], 0, v[8:9]
	v_lshlrev_b32_e32 v10, 1, v6
	v_mov_b32_e32 v11, v101
	v_lshl_add_u64 v[8:9], v[8:9], 0, v[10:11]
	global_load_dwordx4 v[96:99], v[8:9], off
	v_lshl_add_u64 v[254:255], v[8:9], 0, s[48:49]
	global_load_dwordx4 v[226:229], v[254:255], off
.LBB0_539:
	s_or_b64 exec, exec, s[8:9]
	v_mul_lo_u32 v7, v0, s65
	v_add_lshl_u32 v118, v7, v5, 1
	v_mad_u32_u24 v6, v4, s65, v6
	v_mad_u32_u24 v5, v5, s68, v0
	v_lshl_add_u32 v119, v6, 1, v114
	v_add_u32_e32 v6, 0, v118
	v_lshl_add_u32 v120, v5, 1, 0
	s_waitcnt vmcnt(0)
	ds_write_b128 v6, v[88:91]
	ds_write_b128 v6, v[250:253] offset:13312
	s_waitcnt vmcnt(0)
	ds_write_b16 v158, v92 offset:26624
	ds_write_b16_d16_hi v158, v92 offset:26768
	ds_write_b16 v158, v93 offset:26912
	ds_write_b16_d16_hi v158, v93 offset:27056
	ds_write_b16 v158, v94 offset:27200
	ds_write_b16_d16_hi v158, v94 offset:27344
	ds_write_b16 v158, v95 offset:27488
	ds_write_b16_d16_hi v158, v95 offset:27632
	s_and_saveexec_b64 s[8:9], s[6:7]
	v_add_u32_e32 v5, 0, v119
	ds_write_b128 v5, v[96:99]
	ds_write_b128 v5, v[226:229] offset:13312
	s_or_b64 exec, exec, s[8:9]
	v_lshlrev_b32_e32 v5, 3, v3
	v_lshlrev_b32_e32 v117, 2, v3
	v_cmp_eq_u32_e64 s[8:9], 0, v3
	v_mul_u32_u24_e32 v3, 0x90, v116
	s_bfe_u32 s11, s52, 0x20003
	v_add3_u32 v125, 0, v5, v3
	v_and_b32_e32 v3, 3, v2
	v_lshlrev_b32_e32 v4, 6, v4
	s_lshl_b32 s40, s11, 23
	s_mov_b32 s41, s15
	v_lshlrev_b64 v[0:1], 11, v[0:1]
	v_and_b32_e32 v2, 7, v2
	v_mul_u32_u24_e32 v6, 0x68, v116
	v_lshl_or_b32 v4, s11, 18, v4
	v_lshl_add_u64 v[0:1], s[40:41], 0, v[0:1]
	v_lshlrev_b32_e32 v2, 4, v2
	v_add_lshl_u32 v123, v5, v6, 1
	v_lshl_or_b32 v4, v3, 4, v4
	v_mov_b32_e32 v5, v101
	v_or3_b32 v0, v0, s10, v2
	v_mov_b32_e32 v14, v101
	v_mov_b32_e32 v15, v101
	v_lshl_add_u32 v105, v102, 2, 0
	s_lshl_b32 s73, s54, 2
	v_lshl_add_u64 v[106:107], s[28:29], 0, v[4:5]
	v_lshl_add_u64 v[106:107], v[106:107], 0, s[48:49]
	v_lshl_add_u64 v[108:109], s[30:31], 0, v[0:1]
	v_lshl_add_u64 v[108:109], v[108:109], 0, s[50:51]
	v_lshl_add_u64 v[156:157], s[40:41], 0, v[166:167]
	v_or3_b32 v156, v156, s10, v162
	v_lshl_add_u64 v[156:157], s[30:31], 0, v[156:157]
	s_lshl_b32 s10, s53, 2
	v_mov_b32_e32 v0, v101
	v_mov_b32_e32 v1, v101
	v_mov_b32_e32 v2, v101
	v_mov_b32_e32 v3, v101
	v_mov_b32_e32 v4, v101
	v_mov_b32_e32 v6, v101
	v_mov_b32_e32 v7, v101
	v_mov_b32_e32 v8, v101
	v_mov_b32_e32 v9, v101
	v_mov_b32_e32 v10, v101
	v_mov_b32_e32 v11, v101
	v_mov_b32_e32 v12, v101
	v_mov_b32_e32 v13, v101
	v_mov_b64_e32 v[30:31], v[14:15]
	s_add_i32 s73, s73, 4
	v_or_b32_e32 v122, 31, v103
	v_lshl_add_u32 v121, v116, 2, v105
	s_mov_b32 s74, 1
	v_add_u32_e32 v124, 0x1a00, v123
	s_sub_i32 s75, s10, 64
	v_mov_b32_e32 v132, 0xf149f2ca
	v_mov_b32_e32 v126, 0
	s_mov_b32 s76, 63
	v_mov_b64_e32 v[28:29], v[12:13]
	v_mov_b64_e32 v[26:27], v[10:11]
	v_mov_b64_e32 v[24:25], v[8:9]
	v_mov_b64_e32 v[22:23], v[6:7]
	v_mov_b64_e32 v[20:21], v[4:5]
	v_mov_b64_e32 v[18:19], v[2:3]
	v_mov_b64_e32 v[16:17], v[0:1]
	s_waitcnt lgkmcnt(0)
	s_barrier
	ds_read_b128 v[218:221], v123
	ds_read_b128 v[222:225], v124
	ds_read_b128 v[226:229], v123 offset:32
	ds_read_b128 v[250:253], v124 offset:32
	ds_read_b128 v[138:141], v123 offset:64
	ds_read_b128 v[142:145], v124 offset:64
	s_waitcnt lgkmcnt(5)
	v_mfma_f32_32x32x16_bf16 v[48:63], v[218:221], v[64:67], 0
	ds_read_b128 v[218:221], v123 offset:96
	s_waitcnt lgkmcnt(5)
	v_mfma_f32_32x32x16_bf16 v[32:47], v[222:225], v[64:67], 0
	ds_read_b128 v[222:225], v124 offset:96
	s_waitcnt lgkmcnt(5)
	v_mfma_f32_32x32x16_bf16 v[48:63], v[226:229], v[68:71], v[48:63]
	ds_read_b128 v[226:229], v123 offset:128
	s_waitcnt lgkmcnt(5)
	v_mfma_f32_32x32x16_bf16 v[32:47], v[250:253], v[68:71], v[32:47]
	ds_read_b128 v[250:253], v124 offset:128
	s_waitcnt lgkmcnt(5)
	v_mfma_f32_32x32x16_bf16 v[48:63], v[138:141], v[72:75], v[48:63]
	ds_read_b128 v[138:141], v123 offset:160
	s_waitcnt lgkmcnt(5)
	v_mfma_f32_32x32x16_bf16 v[32:47], v[142:145], v[72:75], v[32:47]
	ds_read_b128 v[142:145], v124 offset:160
	s_waitcnt lgkmcnt(5)
	v_mfma_f32_32x32x16_bf16 v[48:63], v[218:221], v[76:79], v[48:63]
	s_waitcnt lgkmcnt(4)
	v_mfma_f32_32x32x16_bf16 v[32:47], v[222:225], v[76:79], v[32:47]
	s_waitcnt lgkmcnt(3)
	v_mfma_f32_32x32x16_bf16 v[48:63], v[226:229], v[80:83], v[48:63]
	s_waitcnt lgkmcnt(2)
	v_mfma_f32_32x32x16_bf16 v[32:47], v[250:253], v[80:83], v[32:47]
	s_waitcnt lgkmcnt(1)
	v_mfma_f32_32x32x16_bf16 v[48:63], v[138:141], v[84:87], v[48:63]
	s_waitcnt lgkmcnt(0)
	v_mfma_f32_32x32x16_bf16 v[32:47], v[142:145], v[84:87], v[32:47]
	s_branch .LBB0_544

.LBB0_544:
	s_cmp_lt_u32 s74, s73
	s_cselect_b64 s[52:53], -1, 0
	s_cmp_ge_u32 s74, s73
	s_cbranch_scc1 .LBB0_548
	global_load_dwordx4 v[92:95], v[156:157], off offset:128
	s_add_i32 s10, s74, 1
	s_cmp_ge_u32 s10, s73
	s_cbranch_scc1 .LBB0_548
	global_load_dwordx4 v[88:91], v[108:109], off
	s_and_saveexec_b64 s[10:11], s[6:7]
	s_cbranch_execz .LBB0_547
	global_load_dwordx4 v[96:99], v[106:107], off

.LBB0_548:
	s_add_i32 s10, s74, -1
	s_and_b32 s77, s10, 1
	s_sub_i32 s10, s76, 63
	v_cmp_le_i32_e32 vcc, s10, v122
	s_and_saveexec_b64 s[54:55], vcc
	s_cbranch_execz .LBB0_556
	s_xor_b32 s10, s77, 1
	s_mul_i32 s10, s10, 0x3400
	v_add_u32_e32 v230, s10, v123
	v_add_u32_e32 v231, s10, v124
	ds_read_b128 v[218:221], v230
	ds_read_b128 v[222:225], v231
	ds_read_b128 v[226:229], v230 offset:32
	ds_read_b128 v[250:253], v231 offset:32
	ds_read_b128 v[138:141], v230 offset:64
	ds_read_b128 v[142:145], v231 offset:64
	v_cmp_gt_i32_e32 vcc, s76, v103
	s_and_saveexec_b64 s[10:11], vcc
	s_cbranch_execz .LBB0_551
	v_add_u32_e32 v127, s76, v117
	v_subrev_u32_e32 v134, 31, v127
	v_subrev_u32_e32 v133, 63, v127
	v_cmp_le_i32_e32 vcc, v134, v104
	s_nop 5
	v_cndmask_b32_e32 v32, v115, v32, vcc
	v_cmp_lt_i32_e32 vcc, v133, v104
	s_nop 1
	v_cndmask_b32_e32 v49, v115, v49, vcc
	v_cmp_le_i32_e32 vcc, v133, v104
	v_subrev_u32_e32 v133, 30, v127
	s_nop 0
	v_cndmask_b32_e32 v48, v115, v48, vcc
	v_cmp_le_i32_e32 vcc, v133, v104
	v_subrev_u32_e32 v133, 61, v127
	s_nop 0
	v_cndmask_b32_e32 v33, v115, v33, vcc
	v_cmp_le_i32_e32 vcc, v133, v104
	v_subrev_u32_e32 v133, 29, v127
	s_nop 0
	v_cndmask_b32_e32 v50, v115, v50, vcc
	v_cmp_le_i32_e32 vcc, v133, v104
	v_subrev_u32_e32 v133, 60, v127
	s_nop 0
	v_cndmask_b32_e32 v34, v115, v34, vcc
	v_cmp_le_i32_e32 vcc, v133, v104
	v_subrev_u32_e32 v133, 28, v127
	s_nop 0
	v_cndmask_b32_e32 v51, v115, v51, vcc
	v_cmp_le_i32_e32 vcc, v133, v104
	v_subrev_u32_e32 v133, 55, v127
	s_nop 0
	v_cndmask_b32_e32 v35, v115, v35, vcc
	v_cmp_le_i32_e32 vcc, v133, v104
	v_subrev_u32_e32 v133, 23, v127
	s_nop 0
	v_cndmask_b32_e32 v52, v115, v52, vcc
	v_cmp_le_i32_e32 vcc, v133, v104
	v_subrev_u32_e32 v133, 54, v127
	s_nop 0
	v_cndmask_b32_e32 v36, v115, v36, vcc
	v_cmp_le_i32_e32 vcc, v133, v104
	v_subrev_u32_e32 v133, 22, v127
	s_nop 0
	v_cndmask_b32_e32 v53, v115, v53, vcc
	v_cmp_le_i32_e32 vcc, v133, v104
	v_subrev_u32_e32 v133, 53, v127
	s_nop 0
	v_cndmask_b32_e32 v37, v115, v37, vcc
	v_cmp_le_i32_e32 vcc, v133, v104
	v_subrev_u32_e32 v133, 21, v127
	s_nop 0
	v_cndmask_b32_e32 v54, v115, v54, vcc
	v_cmp_le_i32_e32 vcc, v133, v104
	v_subrev_u32_e32 v133, 52, v127
	s_nop 0
	v_cndmask_b32_e32 v38, v115, v38, vcc
	v_cmp_le_i32_e32 vcc, v133, v104
	v_subrev_u32_e32 v133, 20, v127
	s_nop 0
	v_cndmask_b32_e32 v55, v115, v55, vcc
	v_cmp_le_i32_e32 vcc, v133, v104
	v_subrev_u32_e32 v133, 47, v127
	s_nop 0
	v_cndmask_b32_e32 v39, v115, v39, vcc
	v_cmp_le_i32_e32 vcc, v133, v104
	v_add_u32_e32 v133, -15, v127
	s_nop 0
	v_cndmask_b32_e32 v56, v115, v56, vcc
	v_cmp_le_i32_e32 vcc, v133, v104
	v_subrev_u32_e32 v133, 46, v127
	s_nop 0
	v_cndmask_b32_e32 v40, v115, v40, vcc
	v_cmp_le_i32_e32 vcc, v133, v104
	v_add_u32_e32 v133, -14, v127
	s_nop 0
	v_cndmask_b32_e32 v57, v115, v57, vcc
	v_cmp_le_i32_e32 vcc, v133, v104
	v_subrev_u32_e32 v133, 45, v127
	s_nop 0
	v_cndmask_b32_e32 v41, v115, v41, vcc
	v_cmp_le_i32_e32 vcc, v133, v104
	v_add_u32_e32 v133, -13, v127
	s_nop 0
	v_cndmask_b32_e32 v58, v115, v58, vcc
	v_cmp_le_i32_e32 vcc, v133, v104
	v_subrev_u32_e32 v133, 44, v127
	s_nop 0
	v_cndmask_b32_e32 v42, v115, v42, vcc
	v_cmp_le_i32_e32 vcc, v133, v104
	v_add_u32_e32 v133, -12, v127
	s_nop 0
	v_cndmask_b32_e32 v59, v115, v59, vcc
	v_cmp_le_i32_e32 vcc, v133, v104
	v_subrev_u32_e32 v133, 39, v127
	s_nop 0
	v_cndmask_b32_e32 v43, v115, v43, vcc
	v_cmp_le_i32_e32 vcc, v133, v104
	v_add_u32_e32 v133, -7, v127
	s_nop 0
	v_cndmask_b32_e32 v60, v115, v60, vcc
	v_cmp_le_i32_e32 vcc, v133, v104
	v_subrev_u32_e32 v133, 38, v127
	s_nop 0
	v_cndmask_b32_e32 v44, v115, v44, vcc
	v_cmp_le_i32_e32 vcc, v133, v104
	v_add_u32_e32 v133, -6, v127
	s_nop 0
	v_cndmask_b32_e32 v61, v115, v61, vcc
	v_cmp_le_i32_e32 vcc, v133, v104
	v_subrev_u32_e32 v133, 37, v127
	s_nop 0
	v_cndmask_b32_e32 v45, v115, v45, vcc
	v_cmp_le_i32_e32 vcc, v133, v104
	v_add_u32_e32 v133, -5, v127
	s_nop 0
	v_cndmask_b32_e32 v62, v115, v62, vcc
	v_cmp_le_i32_e32 vcc, v133, v104
	v_subrev_u32_e32 v133, 36, v127
	v_add_u32_e32 v127, -4, v127
	v_cndmask_b32_e32 v46, v115, v46, vcc
	v_cmp_le_i32_e32 vcc, v133, v104
	s_nop 1
	v_cndmask_b32_e32 v63, v115, v63, vcc
	v_cmp_le_i32_e32 vcc, v127, v104
	s_nop 1
	v_cndmask_b32_e32 v47, v115, v47, vcc
.LBB0_551:
	s_or_b64 exec, exec, s[10:11]
	s_nop 8
	v_max3_f32 v127, v32, v48, s69
	v_max3_f32 v133, v33, v49, s69
	v_max3_f32 v127, v127, v34, v50
	v_max3_f32 v133, v133, v35, v51
	v_max3_f32 v127, v127, v36, v52
	v_max3_f32 v133, v133, v37, v53
	v_max3_f32 v127, v127, v38, v54
	v_max3_f32 v133, v133, v39, v55
	v_max3_f32 v127, v127, v40, v56
	v_max3_f32 v133, v133, v41, v57
	v_max3_f32 v127, v127, v42, v58
	v_max3_f32 v133, v133, v43, v59
	v_max3_f32 v127, v127, v44, v60
	v_max3_f32 v133, v133, v45, v61
	v_max3_f32 v127, v127, v46, v62
	v_max3_f32 v133, v133, v47, v63
	v_max_f32_e32 v127, v127, v133
	v_mov_b32_e32 v133, v127
	s_nop 1
	v_permlane32_swap_b32 v133, v127
	v_max_f32_e32 v127, v127, v133
	v_mul_f32_e32 v127, 0x3e16c740, v127
	v_add_f32_e32 v133, 0x41000000, v132
	v_cmp_gt_f32_e32 vcc, v127, v133
	s_cmp_eq_u64 vcc, 0
	v_max_f32_e32 v133, v132, v132
	v_max_f32_e32 v127, v133, v127
	s_cselect_b64 s[10:11], -1, 0
	v_cndmask_b32_e64 v127, v127, v132, s[10:11]
	v_sub_f32_e32 v132, v132, v127
	v_exp_f32_e32 v132, v132
	s_cbranch_vccz .LBB0_555
	s_and_saveexec_b64 s[10:11], s[8:9]
	ds_write_b32 v121, v132 offset:45056
	s_or_b64 exec, exec, s[10:11]
	s_waitcnt lgkmcnt(0)
	v_add_u32_e32 v133, v105, v100
	ds_read_b128 v[134:137], v133 offset:45152
	ds_read_b128 v[146:149], v133 offset:45056
	s_waitcnt lgkmcnt(0)
	v_pk_mul_f32 v[12:13], v[12:13], v[134:135]
	v_pk_mul_f32 v[14:15], v[14:15], v[136:137]
	v_pk_mul_f32 v[28:29], v[28:29], v[134:135]
	v_pk_mul_f32 v[30:31], v[30:31], v[136:137]
	v_pk_mul_f32 v[2:3], v[2:3], v[148:149]
	v_pk_mul_f32 v[0:1], v[0:1], v[146:147]
	v_pk_mul_f32 v[18:19], v[18:19], v[148:149]
	v_pk_mul_f32 v[16:17], v[16:17], v[146:147]
	ds_read_b128 v[134:137], v133 offset:45120
	ds_read_b128 v[146:149], v133 offset:45088
	s_waitcnt lgkmcnt(0)
	v_pk_mul_f32 v[8:9], v[8:9], v[134:135]
	v_pk_mul_f32 v[10:11], v[10:11], v[136:137]
	v_pk_mul_f32 v[24:25], v[24:25], v[134:135]
	v_pk_mul_f32 v[26:27], v[26:27], v[136:137]
	v_pk_mul_f32 v[4:5], v[4:5], v[146:147]
	v_pk_mul_f32 v[6:7], v[6:7], v[148:149]
	v_pk_mul_f32 v[20:21], v[20:21], v[146:147]
	v_pk_mul_f32 v[22:23], v[22:23], v[148:149]
.LBB0_555:
	s_mul_i32 s10, s77, 0x2400
	v_add_u32_e32 v200, s10, v125
	v_add_u32_e32 v201, 0x7800, v200
	v_add_u32_e32 v200, 0x6800, v200
	ds_read2_b64 v[168:171], v200 offset1:2
	ds_read2_b64 v[172:175], v201 offset0:64 offset1:66
	ds_read2_b64 v[176:179], v200 offset0:4 offset1:6
	ds_read2_b64 v[180:183], v201 offset0:68 offset1:70
	ds_read2_b64 v[184:187], v200 offset0:8 offset1:10
	ds_read2_b64 v[188:191], v201 offset0:72 offset1:74
	ds_read2_b64 v[192:195], v200 offset0:12 offset1:14
	ds_read2_b64 v[196:199], v201 offset0:76 offset1:78
	v_fma_f32 v48, v48, s70, -v127
	s_waitcnt lgkmcnt(13)
	v_mfma_f32_32x32x16_bf16 v[234:249], v[218:221], v[64:67], 0
	ds_read_b128 v[218:221], v230 offset:96
	v_fma_f32 v32, v32, s70, -v127
	v_exp_f32_e32 v48, v48
	v_exp_f32_e32 v133, v32
	s_waitcnt lgkmcnt(13)
	v_mfma_f32_32x32x16_bf16 v[202:217], v[222:225], v[64:67], 0
	ds_read_b128 v[222:225], v231 offset:96
	v_fma_f32 v32, v49, s70, -v127
	v_fma_f32 v33, v33, s70, -v127
	v_exp_f32_e32 v32, v32
	s_waitcnt lgkmcnt(13)
	v_mfma_f32_32x32x16_bf16 v[234:249], v[226:229], v[68:71], v[234:249]
	ds_read_b128 v[226:229], v230 offset:128
	v_exp_f32_e32 v134, v33
	v_fma_f32 v33, v50, s70, -v127
	v_fma_f32 v34, v34, s70, -v127
	s_waitcnt lgkmcnt(13)
	v_mfma_f32_32x32x16_bf16 v[202:217], v[250:253], v[68:71], v[202:217]
	ds_read_b128 v[250:253], v231 offset:128
	v_exp_f32_e32 v33, v33
	v_exp_f32_e32 v50, v34
	v_add_f32_e32 v49, v48, v133
	s_waitcnt lgkmcnt(13)
	v_mfma_f32_32x32x16_bf16 v[234:249], v[138:141], v[72:75], v[234:249]
	ds_read_b128 v[138:141], v230 offset:160
	v_add_f32_e32 v34, 0, v49
	v_add_f32_e32 v49, v32, v134
	v_fma_f32 v51, v51, s70, -v127
	s_waitcnt lgkmcnt(13)
	v_mfma_f32_32x32x16_bf16 v[202:217], v[142:145], v[72:75], v[202:217]
	ds_read_b128 v[142:145], v231 offset:160
	v_fma_f32 v35, v35, s70, -v127
	v_add_f32_e32 v34, v49, v34
	v_add_f32_e32 v49, v33, v50
	v_exp_f32_e32 v51, v51
	v_exp_f32_e32 v135, v35
	v_fma_f32 v35, v52, s70, -v127
	v_fma_f32 v36, v36, s70, -v127
	v_exp_f32_e32 v35, v35
	v_exp_f32_e32 v52, v36
	v_add_f32_e32 v34, v49, v34
	v_fma_f32 v49, v53, s70, -v127
	v_fma_f32 v37, v37, s70, -v127
	v_exp_f32_e32 v49, v49
	v_exp_f32_e32 v53, v37
	s_waitcnt lgkmcnt(5)
	v_mfma_f32_32x32x16_bf16 v[234:249], v[218:221], v[76:79], v[234:249]
	v_fma_f32 v37, v54, s70, -v127
	v_fma_f32 v38, v38, s70, -v127
	v_exp_f32_e32 v37, v37
	v_exp_f32_e32 v54, v38
	v_fma_f32 v38, v55, s70, -v127
	s_waitcnt lgkmcnt(4)
	v_mfma_f32_32x32x16_bf16 v[202:217], v[222:225], v[76:79], v[202:217]
	v_fma_f32 v39, v39, s70, -v127
	v_add_f32_e32 v36, v51, v135
	v_exp_f32_e32 v38, v38
	v_exp_f32_e32 v55, v39
	v_add_f32_e32 v34, v36, v34
	v_add_f32_e32 v36, v35, v52
	s_waitcnt lgkmcnt(3)
	v_mfma_f32_32x32x16_bf16 v[234:249], v[226:229], v[80:83], v[234:249]
	v_add_f32_e32 v34, v36, v34
	v_add_f32_e32 v36, v49, v53
	v_add_f32_e32 v34, v36, v34
	v_add_f32_e32 v36, v37, v54
	v_add_f32_e32 v34, v36, v34
	s_waitcnt lgkmcnt(2)
	v_mfma_f32_32x32x16_bf16 v[202:217], v[250:253], v[80:83], v[202:217]
	v_add_f32_e32 v36, v38, v55
	v_add_f32_e32 v136, v36, v34
	v_fma_f32 v34, v57, s70, -v127
	s_mul_i32 s10, s77, 0x2400
	v_fma_f32 v39, v56, s70, -v127
	v_exp_f32_e32 v57, v34
	s_waitcnt lgkmcnt(1)
	v_mfma_f32_32x32x16_bf16 v[234:249], v[138:141], v[84:87], v[234:249]
	v_fma_f32 v34, v58, s70, -v127
	v_cvt_pk_bf16_f32 v32, v48, v32
	v_add_u32_e32 v48, s10, v125
	v_exp_f32_e32 v56, v39
	v_fma_f32 v39, v40, s70, -v127
	s_waitcnt lgkmcnt(0)
	v_mfma_f32_32x32x16_bf16 v[202:217], v[142:145], v[84:87], v[202:217]
	v_exp_f32_e32 v58, v34
	v_cvt_pk_bf16_f32 v33, v33, v51
	v_cvt_pk_bf16_f32 v34, v35, v49
	v_add_u32_e32 v49, 0x6800, v48
	v_exp_f32_e32 v40, v39
	v_cvt_pk_bf16_f32 v35, v37, v38
	v_add_u32_e32 v48, 0x7800, v48
	v_mfma_f32_32x32x16_bf16 v[0:15], v[32:35], v[168:171], v[0:15]
	v_fma_f32 v59, v59, s70, -v127
	v_exp_f32_e32 v51, v59
	v_fma_f32 v59, v60, s70, -v127
	v_fma_f32 v60, v61, s70, -v127
	v_fma_f32 v61, v62, s70, -v127
	v_fma_f32 v62, v63, s70, -v127
	v_exp_f32_e32 v59, v59
	v_exp_f32_e32 v60, v60
	v_exp_f32_e32 v61, v61
	v_exp_f32_e32 v62, v62
	v_mfma_f32_32x32x16_bf16 v[16:31], v[32:35], v[172:175], v[16:31]
	v_cvt_pk_bf16_f32 v32, v56, v57
	v_cvt_pk_bf16_f32 v33, v58, v51
	v_cvt_pk_bf16_f32 v34, v59, v60
	v_cvt_pk_bf16_f32 v35, v61, v62
	v_fma_f32 v41, v41, s70, -v127
	v_fma_f32 v42, v42, s70, -v127
	v_mfma_f32_32x32x16_bf16 v[0:15], v[32:35], v[176:179], v[0:15]
	v_fma_f32 v43, v43, s70, -v127
	v_fma_f32 v44, v44, s70, -v127
	v_fma_f32 v46, v46, s70, -v127
	v_fma_f32 v47, v47, s70, -v127
	v_exp_f32_e32 v41, v41
	v_exp_f32_e32 v42, v42
	v_mfma_f32_32x32x16_bf16 v[16:31], v[32:35], v[180:183], v[16:31]
	v_cvt_pk_bf16_f32 v32, v133, v134
	v_cvt_pk_bf16_f32 v33, v50, v135
	v_cvt_pk_bf16_f32 v34, v52, v53
	v_cvt_pk_bf16_f32 v35, v54, v55
	v_exp_f32_e32 v43, v43
	v_exp_f32_e32 v44, v44
	v_mfma_f32_32x32x16_bf16 v[0:15], v[32:35], v[184:187], v[0:15]
	v_fma_f32 v36, v45, s70, -v127
	v_exp_f32_e32 v45, v36
	v_exp_f32_e32 v46, v46
	v_exp_f32_e32 v47, v47
	v_add_f32_e32 v137, v56, v40
	v_add_f32_e32 v56, v137, v136
	v_mfma_f32_32x32x16_bf16 v[16:31], v[32:35], v[188:191], v[16:31]
	v_cvt_pk_bf16_f32 v32, v40, v41
	v_cvt_pk_bf16_f32 v33, v42, v43
	v_cvt_pk_bf16_f32 v34, v44, v45
	v_cvt_pk_bf16_f32 v35, v46, v47
	v_add_f32_e32 v57, v57, v41
	v_add_f32_e32 v56, v57, v56
	v_mfma_f32_32x32x16_bf16 v[0:15], v[32:35], v[192:195], v[0:15]
	v_add_f32_e32 v57, v58, v42
	v_add_f32_e32 v50, v57, v56
	v_add_f32_e32 v51, v51, v43
	v_add_f32_e32 v40, v51, v50
	v_add_f32_e32 v41, v59, v44
	v_add_f32_e32 v40, v41, v40
	v_mfma_f32_32x32x16_bf16 v[16:31], v[32:35], v[196:199], v[16:31]
	v_add_f32_e32 v41, v60, v45
	v_add_f32_e32 v40, v41, v40
	v_add_f32_e32 v41, v61, v46
	v_add_f32_e32 v40, v41, v40
	v_add_f32_e32 v41, v62, v47
	v_add_f32_e32 v40, v41, v40
	v_fmac_f32_e32 v40, v126, v132
	v_mov_b32_e32 v132, v127
	v_mov_b32_e32 v126, v40
.LBB0_556:
	s_or_b64 exec, exec, s[54:55]
	s_andn2_b64 vcc, exec, s[52:53]
	s_cbranch_vccnz .Lap0_543
	s_xor_b32 s10, s77, 1
	s_mulk_i32 s10, 0x2400
	v_add_u32_e32 v230, s10, v158
	s_waitcnt vmcnt(0)
	ds_write_b16 v230, v92 offset:26624
	ds_write_b16_d16_hi v230, v92 offset:26768
	ds_write_b16 v230, v93 offset:26912
	ds_write_b16_d16_hi v230, v93 offset:27056
	ds_write_b16 v230, v94 offset:27200
	ds_write_b16_d16_hi v230, v94 offset:27344
	ds_write_b16 v230, v95 offset:27488
	ds_write_b16_d16_hi v230, v95 offset:27632
	s_add_i32 s10, s74, 1
	s_cmp_ge_u32 s10, s73
	s_cbranch_scc1 .Lap0_543
	s_mul_i32 s33, s77, 0x3400
	v_add_u32_e32 v230, s33, v118
	ds_write_b128 v230, v[88:91]
	s_and_saveexec_b64 s[10:11], s[6:7]
	s_cbranch_execz .Lap0_542
	v_add_u32_e32 v230, s33, v119
	ds_write_b128 v230, v[96:99]
	s_branch .Lap0_542

.Lap0_548:
	s_add_i32 s10, s74, -1
	s_and_b32 s77, s10, 1
	s_sub_i32 s10, s76, 63
	v_cmp_le_i32_e32 vcc, s10, v122
	s_and_saveexec_b64 s[54:55], vcc
	s_cbranch_execz .Lap0_556
	s_xor_b32 s10, s77, 1
	s_mul_i32 s10, s10, 0x3400
	v_add_u32_e32 v230, s10, v123
	v_add_u32_e32 v231, s10, v124
	ds_read_b128 v[218:221], v230
	ds_read_b128 v[222:225], v231
	ds_read_b128 v[226:229], v230 offset:32
	ds_read_b128 v[250:253], v231 offset:32
	ds_read_b128 v[138:141], v230 offset:64
	ds_read_b128 v[142:145], v231 offset:64
	v_cmp_gt_i32_e32 vcc, s76, v103
	s_and_saveexec_b64 s[10:11], vcc
	s_cbranch_execz .Lap0_551
	v_add_u32_e32 v127, s76, v117
	v_subrev_u32_e32 v134, 31, v127
	v_subrev_u32_e32 v133, 63, v127
	v_cmp_le_i32_e32 vcc, v134, v104
	s_nop 5
	v_cndmask_b32_e32 v202, v115, v202, vcc
	v_cmp_lt_i32_e32 vcc, v133, v104
	s_nop 1
	v_cndmask_b32_e32 v235, v115, v235, vcc
	v_cmp_le_i32_e32 vcc, v133, v104
	v_subrev_u32_e32 v133, 30, v127
	s_nop 0
	v_cndmask_b32_e32 v234, v115, v234, vcc
	v_cmp_le_i32_e32 vcc, v133, v104
	v_subrev_u32_e32 v133, 61, v127
	s_nop 0
	v_cndmask_b32_e32 v203, v115, v203, vcc
	v_cmp_le_i32_e32 vcc, v133, v104
	v_subrev_u32_e32 v133, 29, v127
	s_nop 0
	v_cndmask_b32_e32 v236, v115, v236, vcc
	v_cmp_le_i32_e32 vcc, v133, v104
	v_subrev_u32_e32 v133, 60, v127
	s_nop 0
	v_cndmask_b32_e32 v204, v115, v204, vcc
	v_cmp_le_i32_e32 vcc, v133, v104
	v_subrev_u32_e32 v133, 28, v127
	s_nop 0
	v_cndmask_b32_e32 v237, v115, v237, vcc
	v_cmp_le_i32_e32 vcc, v133, v104
	v_subrev_u32_e32 v133, 55, v127
	s_nop 0
	v_cndmask_b32_e32 v205, v115, v205, vcc
	v_cmp_le_i32_e32 vcc, v133, v104
	v_subrev_u32_e32 v133, 23, v127
	s_nop 0
	v_cndmask_b32_e32 v238, v115, v238, vcc
	v_cmp_le_i32_e32 vcc, v133, v104
	v_subrev_u32_e32 v133, 54, v127
	s_nop 0
	v_cndmask_b32_e32 v206, v115, v206, vcc
	v_cmp_le_i32_e32 vcc, v133, v104
	v_subrev_u32_e32 v133, 22, v127
	s_nop 0
	v_cndmask_b32_e32 v239, v115, v239, vcc
	v_cmp_le_i32_e32 vcc, v133, v104
	v_subrev_u32_e32 v133, 53, v127
	s_nop 0
	v_cndmask_b32_e32 v207, v115, v207, vcc
	v_cmp_le_i32_e32 vcc, v133, v104
	v_subrev_u32_e32 v133, 21, v127
	s_nop 0
	v_cndmask_b32_e32 v240, v115, v240, vcc
	v_cmp_le_i32_e32 vcc, v133, v104
	v_subrev_u32_e32 v133, 52, v127
	s_nop 0
	v_cndmask_b32_e32 v208, v115, v208, vcc
	v_cmp_le_i32_e32 vcc, v133, v104
	v_subrev_u32_e32 v133, 20, v127
	s_nop 0
	v_cndmask_b32_e32 v241, v115, v241, vcc
	v_cmp_le_i32_e32 vcc, v133, v104
	v_subrev_u32_e32 v133, 47, v127
	s_nop 0
	v_cndmask_b32_e32 v209, v115, v209, vcc
	v_cmp_le_i32_e32 vcc, v133, v104
	v_add_u32_e32 v133, -15, v127
	s_nop 0
	v_cndmask_b32_e32 v242, v115, v242, vcc
	v_cmp_le_i32_e32 vcc, v133, v104
	v_subrev_u32_e32 v133, 46, v127
	s_nop 0
	v_cndmask_b32_e32 v210, v115, v210, vcc
	v_cmp_le_i32_e32 vcc, v133, v104
	v_add_u32_e32 v133, -14, v127
	s_nop 0
	v_cndmask_b32_e32 v243, v115, v243, vcc
	v_cmp_le_i32_e32 vcc, v133, v104
	v_subrev_u32_e32 v133, 45, v127
	s_nop 0
	v_cndmask_b32_e32 v211, v115, v211, vcc
	v_cmp_le_i32_e32 vcc, v133, v104
	v_add_u32_e32 v133, -13, v127
	s_nop 0
	v_cndmask_b32_e32 v244, v115, v244, vcc
	v_cmp_le_i32_e32 vcc, v133, v104
	v_subrev_u32_e32 v133, 44, v127
	s_nop 0
	v_cndmask_b32_e32 v212, v115, v212, vcc
	v_cmp_le_i32_e32 vcc, v133, v104
	v_add_u32_e32 v133, -12, v127
	s_nop 0
	v_cndmask_b32_e32 v245, v115, v245, vcc
	v_cmp_le_i32_e32 vcc, v133, v104
	v_subrev_u32_e32 v133, 39, v127
	s_nop 0
	v_cndmask_b32_e32 v213, v115, v213, vcc
	v_cmp_le_i32_e32 vcc, v133, v104
	v_add_u32_e32 v133, -7, v127
	s_nop 0
	v_cndmask_b32_e32 v246, v115, v246, vcc
	v_cmp_le_i32_e32 vcc, v133, v104
	v_subrev_u32_e32 v133, 38, v127
	s_nop 0
	v_cndmask_b32_e32 v214, v115, v214, vcc
	v_cmp_le_i32_e32 vcc, v133, v104
	v_add_u32_e32 v133, -6, v127
	s_nop 0
	v_cndmask_b32_e32 v247, v115, v247, vcc
	v_cmp_le_i32_e32 vcc, v133, v104
	v_subrev_u32_e32 v133, 37, v127
	s_nop 0
	v_cndmask_b32_e32 v215, v115, v215, vcc
	v_cmp_le_i32_e32 vcc, v133, v104
	v_add_u32_e32 v133, -5, v127
	s_nop 0
	v_cndmask_b32_e32 v248, v115, v248, vcc
	v_cmp_le_i32_e32 vcc, v133, v104
	v_subrev_u32_e32 v133, 36, v127
	v_add_u32_e32 v127, -4, v127
	v_cndmask_b32_e32 v216, v115, v216, vcc
	v_cmp_le_i32_e32 vcc, v133, v104
	s_nop 1
	v_cndmask_b32_e32 v249, v115, v249, vcc
	v_cmp_le_i32_e32 vcc, v127, v104
	s_nop 1
	v_cndmask_b32_e32 v217, v115, v217, vcc
.Lap0_551:
	s_or_b64 exec, exec, s[10:11]
	s_nop 8
	v_max3_f32 v127, v202, v234, s69
	v_max3_f32 v133, v203, v235, s69
	v_max3_f32 v127, v127, v204, v236
	v_max3_f32 v133, v133, v205, v237
	v_max3_f32 v127, v127, v206, v238
	v_max3_f32 v133, v133, v207, v239
	v_max3_f32 v127, v127, v208, v240
	v_max3_f32 v133, v133, v209, v241
	v_max3_f32 v127, v127, v210, v242
	v_max3_f32 v133, v133, v211, v243
	v_max3_f32 v127, v127, v212, v244
	v_max3_f32 v133, v133, v213, v245
	v_max3_f32 v127, v127, v214, v246
	v_max3_f32 v133, v133, v215, v247
	v_max3_f32 v127, v127, v216, v248
	v_max3_f32 v133, v133, v217, v249
	v_max_f32_e32 v127, v127, v133
	v_mov_b32_e32 v133, v127
	s_nop 1
	v_permlane32_swap_b32 v133, v127
	v_max_f32_e32 v127, v127, v133
	v_mul_f32_e32 v127, 0x3e16c740, v127
	v_add_f32_e32 v133, 0x41000000, v132
	v_cmp_gt_f32_e32 vcc, v127, v133
	s_cmp_eq_u64 vcc, 0
	v_max_f32_e32 v133, v132, v132
	v_max_f32_e32 v127, v133, v127
	s_cselect_b64 s[10:11], -1, 0
	v_cndmask_b32_e64 v127, v127, v132, s[10:11]
	v_sub_f32_e32 v132, v132, v127
	v_exp_f32_e32 v132, v132
	s_cbranch_vccz .Lap0_555
	s_and_saveexec_b64 s[10:11], s[8:9]
	ds_write_b32 v121, v132 offset:45056
	s_or_b64 exec, exec, s[10:11]
	s_waitcnt lgkmcnt(0)
	v_add_u32_e32 v133, v105, v100
	ds_read_b128 v[134:137], v133 offset:45152
	ds_read_b128 v[146:149], v133 offset:45056
	s_waitcnt lgkmcnt(0)
	v_pk_mul_f32 v[12:13], v[12:13], v[134:135]
	v_pk_mul_f32 v[14:15], v[14:15], v[136:137]
	v_pk_mul_f32 v[28:29], v[28:29], v[134:135]
	v_pk_mul_f32 v[30:31], v[30:31], v[136:137]
	v_pk_mul_f32 v[2:3], v[2:3], v[148:149]
	v_pk_mul_f32 v[0:1], v[0:1], v[146:147]
	v_pk_mul_f32 v[18:19], v[18:19], v[148:149]
	v_pk_mul_f32 v[16:17], v[16:17], v[146:147]
	ds_read_b128 v[134:137], v133 offset:45120
	ds_read_b128 v[146:149], v133 offset:45088
	s_waitcnt lgkmcnt(0)
	v_pk_mul_f32 v[8:9], v[8:9], v[134:135]
	v_pk_mul_f32 v[10:11], v[10:11], v[136:137]
	v_pk_mul_f32 v[24:25], v[24:25], v[134:135]
	v_pk_mul_f32 v[26:27], v[26:27], v[136:137]
	v_pk_mul_f32 v[4:5], v[4:5], v[146:147]
	v_pk_mul_f32 v[6:7], v[6:7], v[148:149]
	v_pk_mul_f32 v[20:21], v[20:21], v[146:147]
	v_pk_mul_f32 v[22:23], v[22:23], v[148:149]
.Lap0_555:
	s_mul_i32 s10, s77, 0x2400
	v_add_u32_e32 v200, s10, v125
	v_add_u32_e32 v201, 0x7800, v200
	v_add_u32_e32 v200, 0x6800, v200
	ds_read2_b64 v[168:171], v200 offset1:2
	ds_read2_b64 v[172:175], v201 offset0:64 offset1:66
	ds_read2_b64 v[176:179], v200 offset0:4 offset1:6
	ds_read2_b64 v[180:183], v201 offset0:68 offset1:70
	ds_read2_b64 v[184:187], v200 offset0:8 offset1:10
	ds_read2_b64 v[188:191], v201 offset0:72 offset1:74
	ds_read2_b64 v[192:195], v200 offset0:12 offset1:14
	ds_read2_b64 v[196:199], v201 offset0:76 offset1:78
	v_fma_f32 v234, v234, s70, -v127
	s_waitcnt lgkmcnt(13)
	v_mfma_f32_32x32x16_bf16 v[48:63], v[218:221], v[64:67], 0
	ds_read_b128 v[218:221], v230 offset:96
	v_fma_f32 v202, v202, s70, -v127
	v_exp_f32_e32 v234, v234
	v_exp_f32_e32 v133, v202
	s_waitcnt lgkmcnt(13)
	v_mfma_f32_32x32x16_bf16 v[32:47], v[222:225], v[64:67], 0
	ds_read_b128 v[222:225], v231 offset:96
	v_fma_f32 v202, v235, s70, -v127
	v_fma_f32 v203, v203, s70, -v127
	v_exp_f32_e32 v202, v202
	s_waitcnt lgkmcnt(13)
	v_mfma_f32_32x32x16_bf16 v[48:63], v[226:229], v[68:71], v[48:63]
	ds_read_b128 v[226:229], v230 offset:128
	v_exp_f32_e32 v134, v203
	v_fma_f32 v203, v236, s70, -v127
	v_fma_f32 v204, v204, s70, -v127
	s_waitcnt lgkmcnt(13)
	v_mfma_f32_32x32x16_bf16 v[32:47], v[250:253], v[68:71], v[32:47]
	ds_read_b128 v[250:253], v231 offset:128
	v_exp_f32_e32 v203, v203
	v_exp_f32_e32 v236, v204
	v_add_f32_e32 v235, v234, v133
	s_waitcnt lgkmcnt(13)
	v_mfma_f32_32x32x16_bf16 v[48:63], v[138:141], v[72:75], v[48:63]
	ds_read_b128 v[138:141], v230 offset:160
	v_add_f32_e32 v204, 0, v235
	v_add_f32_e32 v235, v202, v134
	v_fma_f32 v237, v237, s70, -v127
	s_waitcnt lgkmcnt(13)
	v_mfma_f32_32x32x16_bf16 v[32:47], v[142:145], v[72:75], v[32:47]
	ds_read_b128 v[142:145], v231 offset:160
	v_fma_f32 v205, v205, s70, -v127
	v_add_f32_e32 v204, v235, v204
	v_add_f32_e32 v235, v203, v236
	v_exp_f32_e32 v237, v237
	v_exp_f32_e32 v135, v205
	v_fma_f32 v205, v238, s70, -v127
	v_fma_f32 v206, v206, s70, -v127
	v_exp_f32_e32 v205, v205
	v_exp_f32_e32 v238, v206
	v_add_f32_e32 v204, v235, v204
	v_fma_f32 v235, v239, s70, -v127
	v_fma_f32 v207, v207, s70, -v127
	v_exp_f32_e32 v235, v235
	v_exp_f32_e32 v239, v207
	s_waitcnt lgkmcnt(5)
	v_mfma_f32_32x32x16_bf16 v[48:63], v[218:221], v[76:79], v[48:63]
	v_fma_f32 v207, v240, s70, -v127
	v_fma_f32 v208, v208, s70, -v127
	v_exp_f32_e32 v207, v207
	v_exp_f32_e32 v240, v208
	v_fma_f32 v208, v241, s70, -v127
	s_waitcnt lgkmcnt(4)
	v_mfma_f32_32x32x16_bf16 v[32:47], v[222:225], v[76:79], v[32:47]
	v_fma_f32 v209, v209, s70, -v127
	v_add_f32_e32 v206, v237, v135
	v_exp_f32_e32 v208, v208
	v_exp_f32_e32 v241, v209
	v_add_f32_e32 v204, v206, v204
	v_add_f32_e32 v206, v205, v238
	s_waitcnt lgkmcnt(3)
	v_mfma_f32_32x32x16_bf16 v[48:63], v[226:229], v[80:83], v[48:63]
	v_add_f32_e32 v204, v206, v204
	v_add_f32_e32 v206, v235, v239
	v_add_f32_e32 v204, v206, v204
	v_add_f32_e32 v206, v207, v240
	v_add_f32_e32 v204, v206, v204
	s_waitcnt lgkmcnt(2)
	v_mfma_f32_32x32x16_bf16 v[32:47], v[250:253], v[80:83], v[32:47]
	v_add_f32_e32 v206, v208, v241
	v_add_f32_e32 v136, v206, v204
	v_fma_f32 v204, v243, s70, -v127
	s_mul_i32 s10, s77, 0x2400
	v_fma_f32 v209, v242, s70, -v127
	v_exp_f32_e32 v243, v204
	s_waitcnt lgkmcnt(1)
	v_mfma_f32_32x32x16_bf16 v[48:63], v[138:141], v[84:87], v[48:63]
	v_fma_f32 v204, v244, s70, -v127
	v_cvt_pk_bf16_f32 v202, v234, v202
	v_add_u32_e32 v234, s10, v125
	v_exp_f32_e32 v242, v209
	v_fma_f32 v209, v210, s70, -v127
	s_waitcnt lgkmcnt(0)
	v_mfma_f32_32x32x16_bf16 v[32:47], v[142:145], v[84:87], v[32:47]
	v_exp_f32_e32 v244, v204
	v_cvt_pk_bf16_f32 v203, v203, v237
	v_cvt_pk_bf16_f32 v204, v205, v235
	v_add_u32_e32 v235, 0x6800, v234
	v_exp_f32_e32 v210, v209
	v_cvt_pk_bf16_f32 v205, v207, v208
	v_add_u32_e32 v234, 0x7800, v234
	v_mfma_f32_32x32x16_bf16 v[0:15], v[202:205], v[168:171], v[0:15]
	v_fma_f32 v245, v245, s70, -v127
	v_exp_f32_e32 v237, v245
	v_fma_f32 v245, v246, s70, -v127
	v_fma_f32 v246, v247, s70, -v127
	v_fma_f32 v247, v248, s70, -v127
	v_fma_f32 v248, v249, s70, -v127
	v_exp_f32_e32 v245, v245
	v_exp_f32_e32 v246, v246
	v_exp_f32_e32 v247, v247
	v_exp_f32_e32 v248, v248
	v_mfma_f32_32x32x16_bf16 v[16:31], v[202:205], v[172:175], v[16:31]
	v_cvt_pk_bf16_f32 v202, v242, v243
	v_cvt_pk_bf16_f32 v203, v244, v237
	v_cvt_pk_bf16_f32 v204, v245, v246
	v_cvt_pk_bf16_f32 v205, v247, v248
	v_fma_f32 v211, v211, s70, -v127
	v_fma_f32 v212, v212, s70, -v127
	v_mfma_f32_32x32x16_bf16 v[0:15], v[202:205], v[176:179], v[0:15]
	v_fma_f32 v213, v213, s70, -v127
	v_fma_f32 v214, v214, s70, -v127
	v_fma_f32 v216, v216, s70, -v127
	v_fma_f32 v217, v217, s70, -v127
	v_exp_f32_e32 v211, v211
	v_exp_f32_e32 v212, v212
	v_mfma_f32_32x32x16_bf16 v[16:31], v[202:205], v[180:183], v[16:31]
	v_cvt_pk_bf16_f32 v202, v133, v134
	v_cvt_pk_bf16_f32 v203, v236, v135
	v_cvt_pk_bf16_f32 v204, v238, v239
	v_cvt_pk_bf16_f32 v205, v240, v241
	v_exp_f32_e32 v213, v213
	v_exp_f32_e32 v214, v214
	v_mfma_f32_32x32x16_bf16 v[0:15], v[202:205], v[184:187], v[0:15]
	v_fma_f32 v206, v215, s70, -v127
	v_exp_f32_e32 v215, v206
	v_exp_f32_e32 v216, v216
	v_exp_f32_e32 v217, v217
	v_add_f32_e32 v137, v242, v210
	v_add_f32_e32 v242, v137, v136
	v_mfma_f32_32x32x16_bf16 v[16:31], v[202:205], v[188:191], v[16:31]
	v_cvt_pk_bf16_f32 v202, v210, v211
	v_cvt_pk_bf16_f32 v203, v212, v213
	v_cvt_pk_bf16_f32 v204, v214, v215
	v_cvt_pk_bf16_f32 v205, v216, v217
	v_add_f32_e32 v243, v243, v211
	v_add_f32_e32 v242, v243, v242
	v_mfma_f32_32x32x16_bf16 v[0:15], v[202:205], v[192:195], v[0:15]
	v_add_f32_e32 v243, v244, v212
	v_add_f32_e32 v236, v243, v242
	v_add_f32_e32 v237, v237, v213
	v_add_f32_e32 v210, v237, v236
	v_add_f32_e32 v211, v245, v214
	v_add_f32_e32 v210, v211, v210
	v_mfma_f32_32x32x16_bf16 v[16:31], v[202:205], v[196:199], v[16:31]
	v_add_f32_e32 v211, v246, v215
	v_add_f32_e32 v210, v211, v210
	v_add_f32_e32 v211, v247, v216
	v_add_f32_e32 v210, v211, v210
	v_add_f32_e32 v211, v248, v217
	v_add_f32_e32 v210, v211, v210
	v_fmac_f32_e32 v210, v126, v132
	v_mov_b32_e32 v132, v127
	v_mov_b32_e32 v126, v210

	.amdhsa_kernel _Z9hymba_fwd6Params
		.amdhsa_group_segment_fixed_size 0
		.amdhsa_private_segment_fixed_size 0
		.amdhsa_kernarg_size 488
		.amdhsa_user_sgpr_count 2
		.amdhsa_user_sgpr_dispatch_ptr 0
		.amdhsa_user_sgpr_queue_ptr 0
		.amdhsa_user_sgpr_kernarg_segment_ptr 1
		.amdhsa_user_sgpr_dispatch_id 0
		.amdhsa_user_sgpr_kernarg_preload_length 0
		.amdhsa_user_sgpr_kernarg_preload_offset 0
		.amdhsa_user_sgpr_private_segment_size 0
		.amdhsa_uses_dynamic_stack 0
		.amdhsa_enable_private_segment 0
		.amdhsa_system_sgpr_workgroup_id_x 1
		.amdhsa_system_sgpr_workgroup_id_y 0
		.amdhsa_system_sgpr_workgroup_id_z 0
		.amdhsa_system_sgpr_workgroup_info 0
		.amdhsa_system_vgpr_workitem_id 2
		.amdhsa_next_free_vgpr 256
		.amdhsa_next_free_sgpr 100
		.amdhsa_accum_offset 256
		.amdhsa_reserve_vcc 1
		.amdhsa_float_round_mode_32 0
		.amdhsa_float_round_mode_16_64 0
		.amdhsa_float_denorm_mode_32 3
		.amdhsa_float_denorm_mode_16_64 3
		.amdhsa_dx10_clamp 1
		.amdhsa_ieee_mode 1
		.amdhsa_fp16_overflow 0
		.amdhsa_tg_split 0
		.amdhsa_exception_fp_ieee_invalid_op 0
		.amdhsa_exception_fp_denorm_src 0
		.amdhsa_exception_fp_ieee_div_zero 0
		.amdhsa_exception_fp_ieee_overflow 0
		.amdhsa_exception_fp_ieee_underflow 0
		.amdhsa_exception_fp_ieee_inexact 0
		.amdhsa_exception_int_div_zero 0
	.end_amdhsa_kernel

amdhsa.kernels:
  - .agpr_count:     0
    .args:
      - .offset:         0
        .size:           232
        .value_kind:     by_value
      - .offset:         232
        .size:           4
        .value_kind:     hidden_block_count_x
      - .offset:         236
        .size:           4
        .value_kind:     hidden_block_count_y
      - .offset:         240
        .size:           4
        .value_kind:     hidden_block_count_z
      - .offset:         244
        .size:           2
        .value_kind:     hidden_group_size_x
      - .offset:         246
        .size:           2
        .value_kind:     hidden_group_size_y
      - .offset:         248
        .size:           2
        .value_kind:     hidden_group_size_z
      - .offset:         250
        .size:           2
        .value_kind:     hidden_remainder_x
      - .offset:         252
        .size:           2
        .value_kind:     hidden_remainder_y
      - .offset:         254
        .size:           2
        .value_kind:     hidden_remainder_z
      - .offset:         272
        .size:           8
        .value_kind:     hidden_global_offset_x
      - .offset:         280
        .size:           8
        .value_kind:     hidden_global_offset_y
      - .offset:         288
        .size:           8
        .value_kind:     hidden_global_offset_z
      - .offset:         296
        .size:           2
        .value_kind:     hidden_grid_dims
      - .offset:         320
        .size:           8
        .value_kind:     hidden_multigrid_sync_arg
      - .offset:         352
        .size:           4
        .value_kind:     hidden_dynamic_lds_size
    .group_segment_fixed_size: 0
    .kernarg_segment_align: 8
    .kernarg_segment_size: 488
    .language:       OpenCL C
    .language_version:
      - 2
      - 0
    .max_flat_workgroup_size: 512
    .name:           _Z9hymba_fwd6Params
    .private_segment_fixed_size: 0
    .sgpr_count:     106
    .sgpr_spill_count: 4
    .symbol:         _Z9hymba_fwd6Params.kd
    .uniform_work_group_size: 1
    .uses_dynamic_stack: false
    .vgpr_count:     256
    .vgpr_spill_count: 0
    .wavefront_size: 64
